# P0 p0_mod: silu staging loop de-serialised too (32 loads per thread issued together); plus GEMV de-serialisation; on the guarded final
# speedup vs baseline: 1.0109x; 1.0037x over previous
; __device__ __forceinline__ void p0_mod(const Args& a, LAS unsigned char* lds, int bid, int G, int tid) {
;     ...
;         for (int idx = tid; idx < 16384; idx += 512) { const int r = idx >> 10, k = idx & 1023;
;             const float c = r < 8 ? a.in[I_CP][r * 1024 + k] : a.in[I_CS][(r - 8) * 1024 + k];
;             S[k * 16 + r] = c / (1.0f + __expf(-c)); }
.LBB0_9:
	s_and_saveexec_b64 s[22:23], s[6:7]
	s_cbranch_execz .LBB0_14
	s_mov_b64 s[64:65], 0x800
	v_mov_b64_e32 v[134:135], v[6:7]
	v_lshlrev_b32_e32 v136, 2, v4
	v_mov_b32_e32 v137, 0
	v_lshl_add_u64 v[136:137], s[10:11], 0, v[136:137]
	v_lshlrev_b32_e32 v138, 6, v4
	global_load_dword v102, v[134:135], off
	v_lshl_add_u64 v[134:135], v[134:135], 0, s[64:65]
	global_load_dword v103, v[134:135], off
	v_lshl_add_u64 v[134:135], v[134:135], 0, s[64:65]
	global_load_dword v104, v[134:135], off
	v_lshl_add_u64 v[134:135], v[134:135], 0, s[64:65]
	global_load_dword v105, v[134:135], off
	v_lshl_add_u64 v[134:135], v[134:135], 0, s[64:65]
	global_load_dword v106, v[134:135], off
	v_lshl_add_u64 v[134:135], v[134:135], 0, s[64:65]
	global_load_dword v107, v[134:135], off
	v_lshl_add_u64 v[134:135], v[134:135], 0, s[64:65]
	global_load_dword v108, v[134:135], off
	v_lshl_add_u64 v[134:135], v[134:135], 0, s[64:65]
	global_load_dword v109, v[134:135], off
	v_lshl_add_u64 v[134:135], v[134:135], 0, s[64:65]
	global_load_dword v110, v[134:135], off
	v_lshl_add_u64 v[134:135], v[134:135], 0, s[64:65]
	global_load_dword v111, v[134:135], off
	v_lshl_add_u64 v[134:135], v[134:135], 0, s[64:65]
	global_load_dword v112, v[134:135], off
	v_lshl_add_u64 v[134:135], v[134:135], 0, s[64:65]
	global_load_dword v113, v[134:135], off
	v_lshl_add_u64 v[134:135], v[134:135], 0, s[64:65]
	global_load_dword v114, v[134:135], off
	v_lshl_add_u64 v[134:135], v[134:135], 0, s[64:65]
	global_load_dword v115, v[134:135], off
	v_lshl_add_u64 v[134:135], v[134:135], 0, s[64:65]
	global_load_dword v116, v[134:135], off
	v_lshl_add_u64 v[134:135], v[134:135], 0, s[64:65]
	global_load_dword v117, v[134:135], off
	global_load_dword v118, v[136:137], off
	v_lshl_add_u64 v[136:137], v[136:137], 0, s[64:65]
	global_load_dword v119, v[136:137], off
	v_lshl_add_u64 v[136:137], v[136:137], 0, s[64:65]
	global_load_dword v120, v[136:137], off
	v_lshl_add_u64 v[136:137], v[136:137], 0, s[64:65]
	global_load_dword v121, v[136:137], off
	v_lshl_add_u64 v[136:137], v[136:137], 0, s[64:65]
	global_load_dword v122, v[136:137], off
	v_lshl_add_u64 v[136:137], v[136:137], 0, s[64:65]
	global_load_dword v123, v[136:137], off
	v_lshl_add_u64 v[136:137], v[136:137], 0, s[64:65]
	global_load_dword v124, v[136:137], off
	v_lshl_add_u64 v[136:137], v[136:137], 0, s[64:65]
	global_load_dword v125, v[136:137], off
	v_lshl_add_u64 v[136:137], v[136:137], 0, s[64:65]
	global_load_dword v126, v[136:137], off
	v_lshl_add_u64 v[136:137], v[136:137], 0, s[64:65]
	global_load_dword v127, v[136:137], off
	v_lshl_add_u64 v[136:137], v[136:137], 0, s[64:65]
	global_load_dword v128, v[136:137], off
	v_lshl_add_u64 v[136:137], v[136:137], 0, s[64:65]
	global_load_dword v129, v[136:137], off
	v_lshl_add_u64 v[136:137], v[136:137], 0, s[64:65]
	global_load_dword v130, v[136:137], off
	v_lshl_add_u64 v[136:137], v[136:137], 0, s[64:65]
	global_load_dword v131, v[136:137], off
	v_lshl_add_u64 v[136:137], v[136:137], 0, s[64:65]
	global_load_dword v132, v[136:137], off
	v_lshl_add_u64 v[136:137], v[136:137], 0, s[64:65]
	global_load_dword v133, v[136:137], off
	s_waitcnt vmcnt(31)
	v_mul_f32_e32 v140, 0xbfb8aa3b, v102
	v_exp_f32_e32 v140, v140
	s_nop 0
	v_add_f32_e32 v141, 1.0, v140
	v_div_scale_f32 v142, s[62:63], v141, v141, v102
	v_rcp_f32_e32 v143, v142
	v_div_scale_f32 v144, vcc, v102, v141, v102
	v_fma_f32 v145, -v142, v143, 1.0
	v_fmac_f32_e32 v143, v145, v143
	v_mul_f32_e32 v146, v144, v143
	v_fma_f32 v145, -v142, v146, v144
	v_fmac_f32_e32 v146, v145, v143
	v_fma_f32 v142, -v142, v146, v144
	v_div_fmas_f32 v142, v142, v143, v146
	v_div_fixup_f32 v140, v142, v141, v102
	ds_write_b32 v138, v140 offset:0
	s_waitcnt vmcnt(30)
	v_mul_f32_e32 v140, 0xbfb8aa3b, v103
	v_exp_f32_e32 v140, v140
	s_nop 0
	v_add_f32_e32 v141, 1.0, v140
	v_div_scale_f32 v142, s[62:63], v141, v141, v103
	v_rcp_f32_e32 v143, v142
	v_div_scale_f32 v144, vcc, v103, v141, v103
	v_fma_f32 v145, -v142, v143, 1.0
	v_fmac_f32_e32 v143, v145, v143
	v_mul_f32_e32 v146, v144, v143
	v_fma_f32 v145, -v142, v146, v144
	v_fmac_f32_e32 v146, v145, v143
	v_fma_f32 v142, -v142, v146, v144
	v_div_fmas_f32 v142, v142, v143, v146
	v_div_fixup_f32 v140, v142, v141, v103
	ds_write_b32 v138, v140 offset:32768
	s_waitcnt vmcnt(29)
	v_mul_f32_e32 v140, 0xbfb8aa3b, v104
	v_exp_f32_e32 v140, v140
	s_nop 0
	v_add_f32_e32 v141, 1.0, v140
	v_div_scale_f32 v142, s[62:63], v141, v141, v104
	v_rcp_f32_e32 v143, v142
	v_div_scale_f32 v144, vcc, v104, v141, v104
	v_fma_f32 v145, -v142, v143, 1.0
	v_fmac_f32_e32 v143, v145, v143
	v_mul_f32_e32 v146, v144, v143
	v_fma_f32 v145, -v142, v146, v144
	v_fmac_f32_e32 v146, v145, v143
	v_fma_f32 v142, -v142, v146, v144
	v_div_fmas_f32 v142, v142, v143, v146
	v_div_fixup_f32 v140, v142, v141, v104
	ds_write_b32 v138, v140 offset:4
	s_waitcnt vmcnt(28)
	v_mul_f32_e32 v140, 0xbfb8aa3b, v105
	v_exp_f32_e32 v140, v140
	s_nop 0
	v_add_f32_e32 v141, 1.0, v140
	v_div_scale_f32 v142, s[62:63], v141, v141, v105
	v_rcp_f32_e32 v143, v142
	v_div_scale_f32 v144, vcc, v105, v141, v105
	v_fma_f32 v145, -v142, v143, 1.0
	v_fmac_f32_e32 v143, v145, v143
	v_mul_f32_e32 v146, v144, v143
	v_fma_f32 v145, -v142, v146, v144
	v_fmac_f32_e32 v146, v145, v143
	v_fma_f32 v142, -v142, v146, v144
	v_div_fmas_f32 v142, v142, v143, v146
	v_div_fixup_f32 v140, v142, v141, v105
	ds_write_b32 v138, v140 offset:32772
	s_waitcnt vmcnt(27)
; __device__ __forceinline__ void p0_mod(const Args& a, LAS unsigned char* lds, int bid, int G, int tid) {
;     ...
;         for (int idx = tid; idx < 16384; idx += 512) { const int r = idx >> 10, k = idx & 1023;
;             const float c = r < 8 ? a.in[I_CP][r * 1024 + k] : a.in[I_CS][(r - 8) * 1024 + k];
;             S[k * 16 + r] = c / (1.0f + __expf(-c)); }
	v_mul_f32_e32 v140, 0xbfb8aa3b, v106
	v_exp_f32_e32 v140, v140
	s_nop 0
	v_add_f32_e32 v141, 1.0, v140
	v_div_scale_f32 v142, s[62:63], v141, v141, v106
	v_rcp_f32_e32 v143, v142
	v_div_scale_f32 v144, vcc, v106, v141, v106
	v_fma_f32 v145, -v142, v143, 1.0
	v_fmac_f32_e32 v143, v145, v143
	v_mul_f32_e32 v146, v144, v143
	v_fma_f32 v145, -v142, v146, v144
	v_fmac_f32_e32 v146, v145, v143
	v_fma_f32 v142, -v142, v146, v144
	v_div_fmas_f32 v142, v142, v143, v146
	v_div_fixup_f32 v140, v142, v141, v106
	ds_write_b32 v138, v140 offset:8
	s_waitcnt vmcnt(26)
	v_mul_f32_e32 v140, 0xbfb8aa3b, v107
	v_exp_f32_e32 v140, v140
	s_nop 0
	v_add_f32_e32 v141, 1.0, v140
	v_div_scale_f32 v142, s[62:63], v141, v141, v107
	v_rcp_f32_e32 v143, v142
	v_div_scale_f32 v144, vcc, v107, v141, v107
	v_fma_f32 v145, -v142, v143, 1.0
	v_fmac_f32_e32 v143, v145, v143
	v_mul_f32_e32 v146, v144, v143
	v_fma_f32 v145, -v142, v146, v144
	v_fmac_f32_e32 v146, v145, v143
	v_fma_f32 v142, -v142, v146, v144
	v_div_fmas_f32 v142, v142, v143, v146
	v_div_fixup_f32 v140, v142, v141, v107
	ds_write_b32 v138, v140 offset:32776
	s_waitcnt vmcnt(25)
	v_mul_f32_e32 v140, 0xbfb8aa3b, v108
	v_exp_f32_e32 v140, v140
	s_nop 0
	v_add_f32_e32 v141, 1.0, v140
	v_div_scale_f32 v142, s[62:63], v141, v141, v108
	v_rcp_f32_e32 v143, v142
	v_div_scale_f32 v144, vcc, v108, v141, v108
	v_fma_f32 v145, -v142, v143, 1.0
	v_fmac_f32_e32 v143, v145, v143
	v_mul_f32_e32 v146, v144, v143
	v_fma_f32 v145, -v142, v146, v144
	v_fmac_f32_e32 v146, v145, v143
	v_fma_f32 v142, -v142, v146, v144
	v_div_fmas_f32 v142, v142, v143, v146
	v_div_fixup_f32 v140, v142, v141, v108
	ds_write_b32 v138, v140 offset:12
	s_waitcnt vmcnt(24)
	v_mul_f32_e32 v140, 0xbfb8aa3b, v109
	v_exp_f32_e32 v140, v140
	s_nop 0
	v_add_f32_e32 v141, 1.0, v140
	v_div_scale_f32 v142, s[62:63], v141, v141, v109
	v_rcp_f32_e32 v143, v142
	v_div_scale_f32 v144, vcc, v109, v141, v109
	v_fma_f32 v145, -v142, v143, 1.0
	v_fmac_f32_e32 v143, v145, v143
	v_mul_f32_e32 v146, v144, v143
	v_fma_f32 v145, -v142, v146, v144
	v_fmac_f32_e32 v146, v145, v143
	v_fma_f32 v142, -v142, v146, v144
	v_div_fmas_f32 v142, v142, v143, v146
	v_div_fixup_f32 v140, v142, v141, v109
	ds_write_b32 v138, v140 offset:32780
	s_waitcnt vmcnt(23)
	v_mul_f32_e32 v140, 0xbfb8aa3b, v110
	v_exp_f32_e32 v140, v140
	s_nop 0
	v_add_f32_e32 v141, 1.0, v140
	v_div_scale_f32 v142, s[62:63], v141, v141, v110
	v_rcp_f32_e32 v143, v142
	v_div_scale_f32 v144, vcc, v110, v141, v110
	v_fma_f32 v145, -v142, v143, 1.0
	v_fmac_f32_e32 v143, v145, v143
	v_mul_f32_e32 v146, v144, v143
	v_fma_f32 v145, -v142, v146, v144
	v_fmac_f32_e32 v146, v145, v143
	v_fma_f32 v142, -v142, v146, v144
	v_div_fmas_f32 v142, v142, v143, v146
	v_div_fixup_f32 v140, v142, v141, v110
	ds_write_b32 v138, v140 offset:16
	s_waitcnt vmcnt(22)
	v_mul_f32_e32 v140, 0xbfb8aa3b, v111
	v_exp_f32_e32 v140, v140
	s_nop 0
	v_add_f32_e32 v141, 1.0, v140
	v_div_scale_f32 v142, s[62:63], v141, v141, v111
	v_rcp_f32_e32 v143, v142
	v_div_scale_f32 v144, vcc, v111, v141, v111
	v_fma_f32 v145, -v142, v143, 1.0
	v_fmac_f32_e32 v143, v145, v143
	v_mul_f32_e32 v146, v144, v143
	v_fma_f32 v145, -v142, v146, v144
	v_fmac_f32_e32 v146, v145, v143
	v_fma_f32 v142, -v142, v146, v144
	v_div_fmas_f32 v142, v142, v143, v146
	v_div_fixup_f32 v140, v142, v141, v111
	ds_write_b32 v138, v140 offset:32784
	s_waitcnt vmcnt(21)
	v_mul_f32_e32 v140, 0xbfb8aa3b, v112
	v_exp_f32_e32 v140, v140
	s_nop 0
	v_add_f32_e32 v141, 1.0, v140
	v_div_scale_f32 v142, s[62:63], v141, v141, v112
	v_rcp_f32_e32 v143, v142
	v_div_scale_f32 v144, vcc, v112, v141, v112
	v_fma_f32 v145, -v142, v143, 1.0
	v_fmac_f32_e32 v143, v145, v143
	v_mul_f32_e32 v146, v144, v143
	v_fma_f32 v145, -v142, v146, v144
	v_fmac_f32_e32 v146, v145, v143
	v_fma_f32 v142, -v142, v146, v144
	v_div_fmas_f32 v142, v142, v143, v146
	v_div_fixup_f32 v140, v142, v141, v112
	ds_write_b32 v138, v140 offset:20
	s_waitcnt vmcnt(20)
	v_mul_f32_e32 v140, 0xbfb8aa3b, v113
	v_exp_f32_e32 v140, v140
	s_nop 0
	v_add_f32_e32 v141, 1.0, v140
	v_div_scale_f32 v142, s[62:63], v141, v141, v113
	v_rcp_f32_e32 v143, v142
	v_div_scale_f32 v144, vcc, v113, v141, v113
	v_fma_f32 v145, -v142, v143, 1.0
	v_fmac_f32_e32 v143, v145, v143
	v_mul_f32_e32 v146, v144, v143
	v_fma_f32 v145, -v142, v146, v144
	v_fmac_f32_e32 v146, v145, v143
	v_fma_f32 v142, -v142, v146, v144
	v_div_fmas_f32 v142, v142, v143, v146
	v_div_fixup_f32 v140, v142, v141, v113
	ds_write_b32 v138, v140 offset:32788
	s_waitcnt vmcnt(19)
	v_mul_f32_e32 v140, 0xbfb8aa3b, v114
	v_exp_f32_e32 v140, v140
	s_nop 0
	v_add_f32_e32 v141, 1.0, v140
	v_div_scale_f32 v142, s[62:63], v141, v141, v114
	v_rcp_f32_e32 v143, v142
	v_div_scale_f32 v144, vcc, v114, v141, v114
	v_fma_f32 v145, -v142, v143, 1.0
	v_fmac_f32_e32 v143, v145, v143
	v_mul_f32_e32 v146, v144, v143
	v_fma_f32 v145, -v142, v146, v144
	v_fmac_f32_e32 v146, v145, v143
	v_fma_f32 v142, -v142, v146, v144
	v_div_fmas_f32 v142, v142, v143, v146
	v_div_fixup_f32 v140, v142, v141, v114
	ds_write_b32 v138, v140 offset:24
	s_waitcnt vmcnt(18)
	v_mul_f32_e32 v140, 0xbfb8aa3b, v115
	v_exp_f32_e32 v140, v140
	s_nop 0
	v_add_f32_e32 v141, 1.0, v140
	v_div_scale_f32 v142, s[62:63], v141, v141, v115
	v_rcp_f32_e32 v143, v142
	v_div_scale_f32 v144, vcc, v115, v141, v115
	v_fma_f32 v145, -v142, v143, 1.0
	v_fmac_f32_e32 v143, v145, v143
	v_mul_f32_e32 v146, v144, v143
	v_fma_f32 v145, -v142, v146, v144
	v_fmac_f32_e32 v146, v145, v143
	v_fma_f32 v142, -v142, v146, v144
	v_div_fmas_f32 v142, v142, v143, v146
	v_div_fixup_f32 v140, v142, v141, v115
	ds_write_b32 v138, v140 offset:32792
	s_waitcnt vmcnt(17)
; __device__ __forceinline__ void p0_mod(const Args& a, LAS unsigned char* lds, int bid, int G, int tid) {
;     ...
;         for (int idx = tid; idx < 16384; idx += 512) { const int r = idx >> 10, k = idx & 1023;
;             const float c = r < 8 ? a.in[I_CP][r * 1024 + k] : a.in[I_CS][(r - 8) * 1024 + k];
;             S[k * 16 + r] = c / (1.0f + __expf(-c)); }
	v_mul_f32_e32 v140, 0xbfb8aa3b, v116
	v_exp_f32_e32 v140, v140
	s_nop 0
	v_add_f32_e32 v141, 1.0, v140
	v_div_scale_f32 v142, s[62:63], v141, v141, v116
	v_rcp_f32_e32 v143, v142
	v_div_scale_f32 v144, vcc, v116, v141, v116
	v_fma_f32 v145, -v142, v143, 1.0
	v_fmac_f32_e32 v143, v145, v143
	v_mul_f32_e32 v146, v144, v143
	v_fma_f32 v145, -v142, v146, v144
	v_fmac_f32_e32 v146, v145, v143
	v_fma_f32 v142, -v142, v146, v144
	v_div_fmas_f32 v142, v142, v143, v146
	v_div_fixup_f32 v140, v142, v141, v116
	ds_write_b32 v138, v140 offset:28
	s_waitcnt vmcnt(16)
	v_mul_f32_e32 v140, 0xbfb8aa3b, v117
	v_exp_f32_e32 v140, v140
	s_nop 0
	v_add_f32_e32 v141, 1.0, v140
	v_div_scale_f32 v142, s[62:63], v141, v141, v117
	v_rcp_f32_e32 v143, v142
	v_div_scale_f32 v144, vcc, v117, v141, v117
	v_fma_f32 v145, -v142, v143, 1.0
	v_fmac_f32_e32 v143, v145, v143
	v_mul_f32_e32 v146, v144, v143
	v_fma_f32 v145, -v142, v146, v144
	v_fmac_f32_e32 v146, v145, v143
	v_fma_f32 v142, -v142, v146, v144
	v_div_fmas_f32 v142, v142, v143, v146
	v_div_fixup_f32 v140, v142, v141, v117
	ds_write_b32 v138, v140 offset:32796
	s_waitcnt vmcnt(15)
	v_mul_f32_e32 v140, 0xbfb8aa3b, v118
	v_exp_f32_e32 v140, v140
	s_nop 0
	v_add_f32_e32 v141, 1.0, v140
	v_div_scale_f32 v142, s[62:63], v141, v141, v118
	v_rcp_f32_e32 v143, v142
	v_div_scale_f32 v144, vcc, v118, v141, v118
	v_fma_f32 v145, -v142, v143, 1.0
	v_fmac_f32_e32 v143, v145, v143
	v_mul_f32_e32 v146, v144, v143
	v_fma_f32 v145, -v142, v146, v144
	v_fmac_f32_e32 v146, v145, v143
	v_fma_f32 v142, -v142, v146, v144
	v_div_fmas_f32 v142, v142, v143, v146
	v_div_fixup_f32 v140, v142, v141, v118
	ds_write_b32 v138, v140 offset:32
	s_waitcnt vmcnt(14)
	v_mul_f32_e32 v140, 0xbfb8aa3b, v119
	v_exp_f32_e32 v140, v140
	s_nop 0
	v_add_f32_e32 v141, 1.0, v140
	v_div_scale_f32 v142, s[62:63], v141, v141, v119
	v_rcp_f32_e32 v143, v142
	v_div_scale_f32 v144, vcc, v119, v141, v119
	v_fma_f32 v145, -v142, v143, 1.0
	v_fmac_f32_e32 v143, v145, v143
	v_mul_f32_e32 v146, v144, v143
	v_fma_f32 v145, -v142, v146, v144
	v_fmac_f32_e32 v146, v145, v143
	v_fma_f32 v142, -v142, v146, v144
	v_div_fmas_f32 v142, v142, v143, v146
	v_div_fixup_f32 v140, v142, v141, v119
	ds_write_b32 v138, v140 offset:32800
	s_waitcnt vmcnt(13)
	v_mul_f32_e32 v140, 0xbfb8aa3b, v120
	v_exp_f32_e32 v140, v140
	s_nop 0
	v_add_f32_e32 v141, 1.0, v140
	v_div_scale_f32 v142, s[62:63], v141, v141, v120
	v_rcp_f32_e32 v143, v142
	v_div_scale_f32 v144, vcc, v120, v141, v120
	v_fma_f32 v145, -v142, v143, 1.0
	v_fmac_f32_e32 v143, v145, v143
	v_mul_f32_e32 v146, v144, v143
	v_fma_f32 v145, -v142, v146, v144
	v_fmac_f32_e32 v146, v145, v143
	v_fma_f32 v142, -v142, v146, v144
	v_div_fmas_f32 v142, v142, v143, v146
	v_div_fixup_f32 v140, v142, v141, v120
	ds_write_b32 v138, v140 offset:36
	s_waitcnt vmcnt(12)
	v_mul_f32_e32 v140, 0xbfb8aa3b, v121
	v_exp_f32_e32 v140, v140
	s_nop 0
	v_add_f32_e32 v141, 1.0, v140
	v_div_scale_f32 v142, s[62:63], v141, v141, v121
	v_rcp_f32_e32 v143, v142
	v_div_scale_f32 v144, vcc, v121, v141, v121
	v_fma_f32 v145, -v142, v143, 1.0
	v_fmac_f32_e32 v143, v145, v143
	v_mul_f32_e32 v146, v144, v143
	v_fma_f32 v145, -v142, v146, v144
	v_fmac_f32_e32 v146, v145, v143
	v_fma_f32 v142, -v142, v146, v144
	v_div_fmas_f32 v142, v142, v143, v146
	v_div_fixup_f32 v140, v142, v141, v121
	ds_write_b32 v138, v140 offset:32804
	s_waitcnt vmcnt(11)
	v_mul_f32_e32 v140, 0xbfb8aa3b, v122
	v_exp_f32_e32 v140, v140
	s_nop 0
	v_add_f32_e32 v141, 1.0, v140
	v_div_scale_f32 v142, s[62:63], v141, v141, v122
	v_rcp_f32_e32 v143, v142
	v_div_scale_f32 v144, vcc, v122, v141, v122
	v_fma_f32 v145, -v142, v143, 1.0
	v_fmac_f32_e32 v143, v145, v143
	v_mul_f32_e32 v146, v144, v143
	v_fma_f32 v145, -v142, v146, v144
	v_fmac_f32_e32 v146, v145, v143
	v_fma_f32 v142, -v142, v146, v144
	v_div_fmas_f32 v142, v142, v143, v146
	v_div_fixup_f32 v140, v142, v141, v122
	ds_write_b32 v138, v140 offset:40
	s_waitcnt vmcnt(10)
	v_mul_f32_e32 v140, 0xbfb8aa3b, v123
	v_exp_f32_e32 v140, v140
	s_nop 0
	v_add_f32_e32 v141, 1.0, v140
	v_div_scale_f32 v142, s[62:63], v141, v141, v123
	v_rcp_f32_e32 v143, v142
	v_div_scale_f32 v144, vcc, v123, v141, v123
	v_fma_f32 v145, -v142, v143, 1.0
	v_fmac_f32_e32 v143, v145, v143
	v_mul_f32_e32 v146, v144, v143
	v_fma_f32 v145, -v142, v146, v144
	v_fmac_f32_e32 v146, v145, v143
	v_fma_f32 v142, -v142, v146, v144
	v_div_fmas_f32 v142, v142, v143, v146
	v_div_fixup_f32 v140, v142, v141, v123
	ds_write_b32 v138, v140 offset:32808
	s_waitcnt vmcnt(9)
	v_mul_f32_e32 v140, 0xbfb8aa3b, v124
	v_exp_f32_e32 v140, v140
	s_nop 0
	v_add_f32_e32 v141, 1.0, v140
	v_div_scale_f32 v142, s[62:63], v141, v141, v124
	v_rcp_f32_e32 v143, v142
	v_div_scale_f32 v144, vcc, v124, v141, v124
	v_fma_f32 v145, -v142, v143, 1.0
	v_fmac_f32_e32 v143, v145, v143
	v_mul_f32_e32 v146, v144, v143
	v_fma_f32 v145, -v142, v146, v144
	v_fmac_f32_e32 v146, v145, v143
	v_fma_f32 v142, -v142, v146, v144
	v_div_fmas_f32 v142, v142, v143, v146
	v_div_fixup_f32 v140, v142, v141, v124
	ds_write_b32 v138, v140 offset:44
	s_waitcnt vmcnt(8)
; __device__ __forceinline__ void p0_mod(const Args& a, LAS unsigned char* lds, int bid, int G, int tid) {
;     ...
;         for (int idx = tid; idx < 16384; idx += 512) { const int r = idx >> 10, k = idx & 1023;
;             const float c = r < 8 ? a.in[I_CP][r * 1024 + k] : a.in[I_CS][(r - 8) * 1024 + k];
;             S[k * 16 + r] = c / (1.0f + __expf(-c)); }
	v_mul_f32_e32 v140, 0xbfb8aa3b, v125
	v_exp_f32_e32 v140, v140
	s_nop 0
	v_add_f32_e32 v141, 1.0, v140
	v_div_scale_f32 v142, s[62:63], v141, v141, v125
	v_rcp_f32_e32 v143, v142
	v_div_scale_f32 v144, vcc, v125, v141, v125
	v_fma_f32 v145, -v142, v143, 1.0
	v_fmac_f32_e32 v143, v145, v143
	v_mul_f32_e32 v146, v144, v143
	v_fma_f32 v145, -v142, v146, v144
	v_fmac_f32_e32 v146, v145, v143
	v_fma_f32 v142, -v142, v146, v144
	v_div_fmas_f32 v142, v142, v143, v146
	v_div_fixup_f32 v140, v142, v141, v125
	ds_write_b32 v138, v140 offset:32812
	s_waitcnt vmcnt(7)
	v_mul_f32_e32 v140, 0xbfb8aa3b, v126
	v_exp_f32_e32 v140, v140
	s_nop 0
	v_add_f32_e32 v141, 1.0, v140
	v_div_scale_f32 v142, s[62:63], v141, v141, v126
	v_rcp_f32_e32 v143, v142
	v_div_scale_f32 v144, vcc, v126, v141, v126
	v_fma_f32 v145, -v142, v143, 1.0
	v_fmac_f32_e32 v143, v145, v143
	v_mul_f32_e32 v146, v144, v143
	v_fma_f32 v145, -v142, v146, v144
	v_fmac_f32_e32 v146, v145, v143
	v_fma_f32 v142, -v142, v146, v144
	v_div_fmas_f32 v142, v142, v143, v146
	v_div_fixup_f32 v140, v142, v141, v126
	ds_write_b32 v138, v140 offset:48
	s_waitcnt vmcnt(6)
	v_mul_f32_e32 v140, 0xbfb8aa3b, v127
	v_exp_f32_e32 v140, v140
	s_nop 0
	v_add_f32_e32 v141, 1.0, v140
	v_div_scale_f32 v142, s[62:63], v141, v141, v127
	v_rcp_f32_e32 v143, v142
	v_div_scale_f32 v144, vcc, v127, v141, v127
	v_fma_f32 v145, -v142, v143, 1.0
	v_fmac_f32_e32 v143, v145, v143
	v_mul_f32_e32 v146, v144, v143
	v_fma_f32 v145, -v142, v146, v144
	v_fmac_f32_e32 v146, v145, v143
	v_fma_f32 v142, -v142, v146, v144
	v_div_fmas_f32 v142, v142, v143, v146
	v_div_fixup_f32 v140, v142, v141, v127
	ds_write_b32 v138, v140 offset:32816
	s_waitcnt vmcnt(5)
	v_mul_f32_e32 v140, 0xbfb8aa3b, v128
	v_exp_f32_e32 v140, v140
	s_nop 0
	v_add_f32_e32 v141, 1.0, v140
	v_div_scale_f32 v142, s[62:63], v141, v141, v128
	v_rcp_f32_e32 v143, v142
	v_div_scale_f32 v144, vcc, v128, v141, v128
	v_fma_f32 v145, -v142, v143, 1.0
	v_fmac_f32_e32 v143, v145, v143
	v_mul_f32_e32 v146, v144, v143
	v_fma_f32 v145, -v142, v146, v144
	v_fmac_f32_e32 v146, v145, v143
	v_fma_f32 v142, -v142, v146, v144
	v_div_fmas_f32 v142, v142, v143, v146
	v_div_fixup_f32 v140, v142, v141, v128
	ds_write_b32 v138, v140 offset:52
	s_waitcnt vmcnt(4)
	v_mul_f32_e32 v140, 0xbfb8aa3b, v129
	v_exp_f32_e32 v140, v140
	s_nop 0
	v_add_f32_e32 v141, 1.0, v140
	v_div_scale_f32 v142, s[62:63], v141, v141, v129
	v_rcp_f32_e32 v143, v142
	v_div_scale_f32 v144, vcc, v129, v141, v129
	v_fma_f32 v145, -v142, v143, 1.0
	v_fmac_f32_e32 v143, v145, v143
	v_mul_f32_e32 v146, v144, v143
	v_fma_f32 v145, -v142, v146, v144
	v_fmac_f32_e32 v146, v145, v143
	v_fma_f32 v142, -v142, v146, v144
	v_div_fmas_f32 v142, v142, v143, v146
	v_div_fixup_f32 v140, v142, v141, v129
	ds_write_b32 v138, v140 offset:32820
	s_waitcnt vmcnt(3)
	v_mul_f32_e32 v140, 0xbfb8aa3b, v130
	v_exp_f32_e32 v140, v140
	s_nop 0
	v_add_f32_e32 v141, 1.0, v140
	v_div_scale_f32 v142, s[62:63], v141, v141, v130
	v_rcp_f32_e32 v143, v142
	v_div_scale_f32 v144, vcc, v130, v141, v130
	v_fma_f32 v145, -v142, v143, 1.0
	v_fmac_f32_e32 v143, v145, v143
	v_mul_f32_e32 v146, v144, v143
	v_fma_f32 v145, -v142, v146, v144
	v_fmac_f32_e32 v146, v145, v143
	v_fma_f32 v142, -v142, v146, v144
	v_div_fmas_f32 v142, v142, v143, v146
	v_div_fixup_f32 v140, v142, v141, v130
	ds_write_b32 v138, v140 offset:56
	s_waitcnt vmcnt(2)
	v_mul_f32_e32 v140, 0xbfb8aa3b, v131
	v_exp_f32_e32 v140, v140
	s_nop 0
	v_add_f32_e32 v141, 1.0, v140
	v_div_scale_f32 v142, s[62:63], v141, v141, v131
	v_rcp_f32_e32 v143, v142
	v_div_scale_f32 v144, vcc, v131, v141, v131
	v_fma_f32 v145, -v142, v143, 1.0
	v_fmac_f32_e32 v143, v145, v143
	v_mul_f32_e32 v146, v144, v143
	v_fma_f32 v145, -v142, v146, v144
	v_fmac_f32_e32 v146, v145, v143
	v_fma_f32 v142, -v142, v146, v144
	v_div_fmas_f32 v142, v142, v143, v146
	v_div_fixup_f32 v140, v142, v141, v131
	ds_write_b32 v138, v140 offset:32824
	s_waitcnt vmcnt(1)
	v_mul_f32_e32 v140, 0xbfb8aa3b, v132
	v_exp_f32_e32 v140, v140
	s_nop 0
	v_add_f32_e32 v141, 1.0, v140
	v_div_scale_f32 v142, s[62:63], v141, v141, v132
	v_rcp_f32_e32 v143, v142
	v_div_scale_f32 v144, vcc, v132, v141, v132
	v_fma_f32 v145, -v142, v143, 1.0
	v_fmac_f32_e32 v143, v145, v143
	v_mul_f32_e32 v146, v144, v143
	v_fma_f32 v145, -v142, v146, v144
	v_fmac_f32_e32 v146, v145, v143
	v_fma_f32 v142, -v142, v146, v144
	v_div_fmas_f32 v142, v142, v143, v146
	v_div_fixup_f32 v140, v142, v141, v132
	ds_write_b32 v138, v140 offset:60
	s_waitcnt vmcnt(0)
	v_mul_f32_e32 v140, 0xbfb8aa3b, v133
	v_exp_f32_e32 v140, v140
	s_nop 0
	v_add_f32_e32 v141, 1.0, v140
	v_div_scale_f32 v142, s[62:63], v141, v141, v133
	v_rcp_f32_e32 v143, v142
	v_div_scale_f32 v144, vcc, v133, v141, v133
	v_fma_f32 v145, -v142, v143, 1.0
	v_fmac_f32_e32 v143, v145, v143
	v_mul_f32_e32 v146, v144, v143
	v_fma_f32 v145, -v142, v146, v144
	v_fmac_f32_e32 v146, v145, v143
	v_fma_f32 v142, -v142, v146, v144
	v_div_fmas_f32 v142, v142, v143, v146
	v_div_fixup_f32 v140, v142, v141, v133
	ds_write_b32 v138, v140 offset:32828
